# attention: loop back edge rotated (step counter, buffer select, next-tile prefetch and dispatch before the step barrier; each body starts right behind its own barrier copy)
# speedup vs baseline: 1.0023x; 1.0023x over previous
; #define LAS __attribute__((address_space(3)))
; __device__ __forceinline__ void attn_phase(LAS unsigned char* lds, const bf16_t* __restrict__ Q, const bf16_t* __restrict__ KN, const bf16_t* __restrict__ KR,
;                                            const bf16_t* __restrict__ VT, bf16_t* AO, int vcu, int G, int tid, int lane, int wave) {
;     ...
;             for (int t = 0; t < NT2; ++t) {
;                 const bool more = (t + 1 < NT2);
;                 const LAS unsigned char* buf = lds + (t & 1) * BUF;
;                 const LAS unsigned char* kA = buf + (pr * KP + 8 * hi) * 2; const LAS unsigned char* vA = buf + KBUF + (r32 * VP + 8 * hi) * 2;
;                 if (2 * t + 1 <= qc) {
;                     bf16x8 kf[12], kf2[12], vf[8], vf2[8], pa[4], pb2[4]; f32x16 a0, a1, b0, b1;
;                     attn_ldk(kf, kA);
;                     __builtin_amdgcn_sched_barrier(0);
;                     attn_qk(a0, a1, kf, qf);
;                     attn_ldk(kf2, kA + 64 * KP * 2);
;                     __builtin_amdgcn_sched_barrier(0);
;                     attn_qk(b0, b1, kf2, qf);
;                     attn_softmax(a0, a1, pa, o0, o1, m_run, l_run);
;                     attn_ldv(vf, vA);
;                     __builtin_amdgcn_sched_barrier(0);
;                     PREFETCH_NEXT();
;                     attn_ldv(vf2, vA + 128);
;                     __builtin_amdgcn_sched_barrier(0);
;                     attn_pv(vf, pa, o0, o1);
;                     attn_softmax(b0, b1, pb2, o0, o1, m_run, l_run);
;                     __builtin_amdgcn_sched_barrier(0);
;                     attn_pv(vf2, pb2, o0, o1);
.Lat_nopf:
	s_lshl_b32 s40, s8, 1
	s_cmp_lt_u32 s40, s33
	s_cbranch_scc1 .Lat_both
	s_cmp_eq_u32 s40, s33
	s_cbranch_scc1 .Lat_single
	s_branch .Lat_tail
.Lat_both_b:
	s_barrier
.Lat_both:
	v_add_u32_e32 v1, s37, v222
	v_add_u32_e32 v225, s37, v223
	ds_read_b128 v[138:141], v1
	ds_read_b128 v[142:145], v1 offset:32
	ds_read_b128 v[146:149], v1 offset:64
	ds_read_b128 v[150:153], v1 offset:96
	ds_read_b128 v[154:157], v1 offset:128
	ds_read_b128 v[158:161], v1 offset:160
	ds_read_b128 v[162:165], v1 offset:6656
	ds_read_b128 v[166:169], v1 offset:6688
	s_waitcnt vmcnt(5)
	s_waitcnt lgkmcnt(7)
	v_mfma_f32_32x32x16_bf16 v[34:49], v[138:141], v[114:117], v[98:113]
	ds_read_b128 v[138:141], v1 offset:6720
	s_waitcnt lgkmcnt(7)
	v_mfma_f32_32x32x16_bf16 v[34:49], v[142:145], v[118:121], v[34:49]
	ds_read_b128 v[142:145], v1 offset:6752
	s_waitcnt lgkmcnt(7)
	v_mfma_f32_32x32x16_bf16 v[34:49], v[146:149], v[122:125], v[34:49]
	ds_read_b128 v[146:149], v1 offset:6784
	s_waitcnt lgkmcnt(7)
	v_mfma_f32_32x32x16_bf16 v[34:49], v[150:153], v[126:129], v[34:49]
	ds_read_b128 v[150:153], v1 offset:6816
	s_waitcnt lgkmcnt(7)
	v_mfma_f32_32x32x16_bf16 v[34:49], v[154:157], v[130:133], v[34:49]
	ds_read_b128 v[154:157], v1 offset:13312
	s_waitcnt lgkmcnt(7)
	v_mfma_f32_32x32x16_bf16 v[34:49], v[158:161], v[134:137], v[34:49]
	ds_read_b128 v[158:161], v1 offset:19968
	s_cmp_lg_u32 s7, 0
	s_cbranch_scc1 .Lat_plain_A2
	s_waitcnt lgkmcnt(7)
	v_mfma_f32_32x32x16_bf16 v[50:65], v[162:165], v[114:117], v[98:113]
	ds_read_b128 v[162:165], v1 offset:13344
	s_waitcnt lgkmcnt(7)
	v_mfma_f32_32x32x16_bf16 v[50:65], v[166:169], v[118:121], v[50:65]
	ds_read_b128 v[166:169], v1 offset:20000
	s_nop 2
	v_exp_f32_e32 v34, v34
	v_exp_f32_e32 v35, v35
	v_exp_f32_e32 v36, v36
	v_exp_f32_e32 v37, v37
	s_waitcnt lgkmcnt(7)
	v_mfma_f32_32x32x16_bf16 v[50:65], v[138:141], v[122:125], v[50:65]
	ds_read_b128 v[138:141], v1 offset:13376
	v_exp_f32_e32 v38, v38
	v_exp_f32_e32 v39, v39
	v_exp_f32_e32 v40, v40
	s_waitcnt lgkmcnt(7)
	v_mfma_f32_32x32x16_bf16 v[50:65], v[142:145], v[126:129], v[50:65]
	ds_read_b128 v[142:145], v1 offset:20032
	v_exp_f32_e32 v41, v41
	v_exp_f32_e32 v42, v42
	v_exp_f32_e32 v43, v43
	s_waitcnt lgkmcnt(7)
	v_mfma_f32_32x32x16_bf16 v[50:65], v[146:149], v[130:133], v[50:65]
	ds_read_b128 v[146:149], v1 offset:13408
	v_exp_f32_e32 v44, v44
	v_exp_f32_e32 v45, v45
	v_exp_f32_e32 v46, v46
	s_waitcnt lgkmcnt(7)
	v_mfma_f32_32x32x16_bf16 v[50:65], v[150:153], v[134:137], v[50:65]
	ds_read_b128 v[150:153], v1 offset:20064
	v_exp_f32_e32 v47, v47
	v_exp_f32_e32 v48, v48
	v_exp_f32_e32 v49, v49
	s_waitcnt lgkmcnt(7)
	v_mfma_f32_32x32x16_bf16 v[66:81], v[154:157], v[114:117], v[98:113]
	ds_read_b128 v[154:157], v1 offset:13440
	s_waitcnt lgkmcnt(7)
	v_mfma_f32_32x32x16_bf16 v[82:97], v[158:161], v[114:117], v[98:113]
	ds_read_b128 v[158:161], v1 offset:20096
	s_nop 1
	v_exp_f32_e32 v50, v50
	v_exp_f32_e32 v51, v51
	v_exp_f32_e32 v52, v52
	v_exp_f32_e32 v53, v53
	s_waitcnt lgkmcnt(7)
	v_mfma_f32_32x32x16_bf16 v[66:81], v[162:165], v[118:121], v[66:81]
	ds_read_b128 v[162:165], v1 offset:13472
	v_exp_f32_e32 v54, v54
	v_exp_f32_e32 v55, v55
	v_exp_f32_e32 v56, v56
	s_waitcnt lgkmcnt(7)
	v_mfma_f32_32x32x16_bf16 v[82:97], v[166:169], v[118:121], v[82:97]
	ds_read_b128 v[166:169], v1 offset:20128
	v_exp_f32_e32 v57, v57
	v_exp_f32_e32 v58, v58
	v_exp_f32_e32 v59, v59
	s_waitcnt lgkmcnt(7)
	v_mfma_f32_32x32x16_bf16 v[66:81], v[138:141], v[122:125], v[66:81]
	ds_read_b128 v[170:173], v225 offset:26624
	v_exp_f32_e32 v60, v60
	v_exp_f32_e32 v61, v61
	v_exp_f32_e32 v62, v62
	s_waitcnt lgkmcnt(7)
	v_mfma_f32_32x32x16_bf16 v[82:97], v[142:145], v[122:125], v[82:97]
	ds_read_b128 v[174:177], v225 offset:35328
	v_exp_f32_e32 v63, v63
	v_exp_f32_e32 v64, v64
	v_exp_f32_e32 v65, v65
	s_waitcnt lgkmcnt(7)
	v_mfma_f32_32x32x16_bf16 v[66:81], v[146:149], v[126:129], v[66:81]
	ds_read_b128 v[178:181], v225 offset:26656
	v_add_f32_e32 v250, v34, v36
	v_add_f32_e32 v251, v35, v37
	v_add_f32_e32 v252, v50, v52
	v_add_f32_e32 v253, v51, v53
	v_add_f32_e32 v250, v250, v38
	v_add_f32_e32 v251, v251, v39
	s_waitcnt lgkmcnt(7)
	v_mfma_f32_32x32x16_bf16 v[82:97], v[150:153], v[126:129], v[82:97]
	ds_read_b128 v[182:185], v225 offset:35360
	v_add_f32_e32 v252, v252, v54
	v_add_f32_e32 v253, v253, v55
	v_add_f32_e32 v250, v250, v40
	v_add_f32_e32 v251, v251, v41
	v_add_f32_e32 v252, v252, v56
	s_waitcnt lgkmcnt(7)
	v_mfma_f32_32x32x16_bf16 v[66:81], v[154:157], v[130:133], v[66:81]
	ds_read_b128 v[186:189], v225 offset:26688
	v_add_f32_e32 v253, v253, v57
	v_add_f32_e32 v250, v250, v42
	v_add_f32_e32 v251, v251, v43
	v_add_f32_e32 v252, v252, v58
	v_add_f32_e32 v253, v253, v59
	s_waitcnt lgkmcnt(7)
	v_mfma_f32_32x32x16_bf16 v[82:97], v[158:161], v[130:133], v[82:97]
	ds_read_b128 v[190:193], v225 offset:35392
	v_add_f32_e32 v250, v250, v44
	v_add_f32_e32 v251, v251, v45
	v_add_f32_e32 v252, v252, v60
	v_add_f32_e32 v253, v253, v61
	v_add_f32_e32 v250, v250, v46
	s_waitcnt lgkmcnt(7)
	v_mfma_f32_32x32x16_bf16 v[66:81], v[162:165], v[134:137], v[66:81]
	v_add_f32_e32 v251, v251, v47
	v_add_f32_e32 v252, v252, v62
	v_add_f32_e32 v253, v253, v63
	v_add_f32_e32 v250, v250, v48
	v_add_f32_e32 v251, v251, v49
	s_waitcnt lgkmcnt(6)
	v_mfma_f32_32x32x16_bf16 v[82:97], v[166:169], v[134:137], v[82:97]
	v_add_f32_e32 v252, v252, v64
	v_add_f32_e32 v253, v253, v65
	v_add_f32_e32 v250, v250, v252
	v_add_f32_e32 v251, v251, v253
	v_add_f32_e32 v1, v250, v251
	s_mov_b32 s41, 0
	s_branch .Lat_sum_A2

; #define LAS __attribute__((address_space(3)))
; __device__ __forceinline__ void attn_phase(LAS unsigned char* lds, const bf16_t* __restrict__ Q, const bf16_t* __restrict__ KN, const bf16_t* __restrict__ KR,
;                                            const bf16_t* __restrict__ VT, bf16_t* AO, int vcu, int G, int tid, int lane, int wave) {
;     ...
;                     attn_ldv(vf2, vA + 128);
;                     __builtin_amdgcn_sched_barrier(0);
;                     attn_pv(vf, pa, o0, o1);
;                     attn_softmax(b0, b1, pb2, o0, o1, m_run, l_run);
;                     __builtin_amdgcn_sched_barrier(0);
;                     attn_pv(vf2, pb2, o0, o1);
;                 } else if (2 * t <= qc) {
;                     bf16x8 kf[12], vf[8], pa[4]; f32x16 a0, a1;
;                     PREFETCH_NEXT();
;                     attn_ldk(kf, kA);
;                     __builtin_amdgcn_sched_barrier(0);
;                     attn_qk(a0, a1, kf, qf);
;                     __builtin_amdgcn_sched_barrier(0);
;                     attn_ldv(vf, vA);
;                     __builtin_amdgcn_sched_barrier(0);
;                     attn_softmax(a0, a1, pa, o0, o1, m_run, l_run);
;                     __builtin_amdgcn_sched_barrier(0);
;                     attn_pv(vf, pa, o0, o1);
;                 } else { PREFETCH_NEXT(); }
;                 if (more) { LAS unsigned char* nb = lds + ((t + 1) & 1) * BUF;
;                     *(LAS u32x4*)(nb + kdst) = gk0; *(LAS u32x4*)(nb + kdst + 64 * KP * 2) = gk1; *(LAS u32x4*)(nb + rdst) = gr; *(LAS u32x4*)(nb + vdst) = gv0; *(LAS u32x4*)(nb + vdst + 128) = gv1; }
.Lat_fast_B2:
	v_add_f32_e32 v227, v227, v1
	v_cvt_pk_bf16_f32 v66, v66, v67
	v_cvt_pk_bf16_f32 v67, v68, v69
	v_cvt_pk_bf16_f32 v68, v70, v71
	v_cvt_pk_bf16_f32 v69, v72, v73
	v_cvt_pk_bf16_f32 v74, v74, v75
	v_cvt_pk_bf16_f32 v75, v76, v77
	v_cvt_pk_bf16_f32 v76, v78, v79
	v_cvt_pk_bf16_f32 v77, v80, v81
	v_cvt_pk_bf16_f32 v82, v82, v83
	v_cvt_pk_bf16_f32 v83, v84, v85
	v_cvt_pk_bf16_f32 v84, v86, v87
	v_cvt_pk_bf16_f32 v85, v88, v89
	v_cvt_pk_bf16_f32 v90, v90, v91
	v_cvt_pk_bf16_f32 v91, v92, v93
	v_cvt_pk_bf16_f32 v92, v94, v95
	v_cvt_pk_bf16_f32 v93, v96, v97
	s_waitcnt lgkmcnt(5)
	v_mfma_f32_32x32x16_bf16 v[2:17], v[178:181], v[66:69], v[2:17]
	ds_read_b128 v[178:181], v225 offset:26848
	s_waitcnt vmcnt(0)
	v_add_u32_e32 v226, s38, v219
	ds_write_b128 v226, v[228:231]
	s_waitcnt lgkmcnt(6)
	v_mfma_f32_32x32x16_bf16 v[18:33], v[182:185], v[66:69], v[18:33]
	ds_read_b128 v[182:185], v225 offset:35552
	ds_write_b128 v226, v[232:235] offset:13312
	s_waitcnt lgkmcnt(7)
	v_mfma_f32_32x32x16_bf16 v[2:17], v[186:189], v[74:77], v[2:17]
	v_add_u32_e32 v226, s38, v220
	ds_write_b128 v226, v[236:239]
	s_waitcnt lgkmcnt(7)
	v_mfma_f32_32x32x16_bf16 v[18:33], v[190:193], v[74:77], v[18:33]
	v_add_u32_e32 v226, s38, v221
	ds_write_b128 v226, v[240:243] offset:26624
	s_waitcnt lgkmcnt(7)
	v_mfma_f32_32x32x16_bf16 v[2:17], v[170:173], v[82:85], v[2:17]
	ds_write_b128 v226, v[244:247] offset:26752
	s_waitcnt lgkmcnt(7)
	v_mfma_f32_32x32x16_bf16 v[18:33], v[174:177], v[82:85], v[18:33]
	s_waitcnt lgkmcnt(6)
	v_mfma_f32_32x32x16_bf16 v[2:17], v[178:181], v[90:93], v[2:17]
	s_waitcnt lgkmcnt(4)
	v_mfma_f32_32x32x16_bf16 v[18:33], v[182:185], v[90:93], v[18:33]
	s_branch .Lat_nostage
.Lat_single_b:
	s_barrier
.Lat_single:
	v_add_u32_e32 v1, s37, v222
	v_add_u32_e32 v225, s37, v223
	ds_read_b128 v[138:141], v1
	ds_read_b128 v[142:145], v1 offset:6656
	ds_read_b128 v[146:149], v1 offset:32
	ds_read_b128 v[150:153], v1 offset:6688
	ds_read_b128 v[154:157], v1 offset:64
	ds_read_b128 v[158:161], v1 offset:6720
	ds_read_b128 v[162:165], v1 offset:96
	ds_read_b128 v[166:169], v1 offset:6752
	s_waitcnt vmcnt(5)
	s_waitcnt lgkmcnt(7)
	v_mfma_f32_32x32x16_bf16 v[34:49], v[138:141], v[114:117], v[98:113]
	ds_read_b128 v[138:141], v1 offset:128
	s_waitcnt lgkmcnt(7)
	v_mfma_f32_32x32x16_bf16 v[50:65], v[142:145], v[114:117], v[98:113]
	ds_read_b128 v[142:145], v1 offset:6784
	s_waitcnt lgkmcnt(7)
	v_mfma_f32_32x32x16_bf16 v[34:49], v[146:149], v[118:121], v[34:49]
	ds_read_b128 v[146:149], v1 offset:160
	s_waitcnt lgkmcnt(7)
	v_mfma_f32_32x32x16_bf16 v[50:65], v[150:153], v[118:121], v[50:65]
	ds_read_b128 v[150:153], v1 offset:6816
	s_waitcnt lgkmcnt(7)
	v_mfma_f32_32x32x16_bf16 v[34:49], v[154:157], v[122:125], v[34:49]
	ds_read_b128 v[170:173], v225 offset:26624
	s_waitcnt lgkmcnt(7)
	v_mfma_f32_32x32x16_bf16 v[50:65], v[158:161], v[122:125], v[50:65]
	ds_read_b128 v[174:177], v225 offset:35328
	s_waitcnt lgkmcnt(7)
	v_mfma_f32_32x32x16_bf16 v[34:49], v[162:165], v[126:129], v[34:49]
	ds_read_b128 v[178:181], v225 offset:26656
	s_waitcnt lgkmcnt(7)
	v_mfma_f32_32x32x16_bf16 v[50:65], v[166:169], v[126:129], v[50:65]
	ds_read_b128 v[182:185], v225 offset:35360
	s_waitcnt lgkmcnt(7)
	v_mfma_f32_32x32x16_bf16 v[34:49], v[138:141], v[130:133], v[34:49]
	ds_read_b128 v[186:189], v225 offset:26688
	s_waitcnt lgkmcnt(7)
	v_mfma_f32_32x32x16_bf16 v[50:65], v[142:145], v[130:133], v[50:65]
	ds_read_b128 v[190:193], v225 offset:35392
	s_waitcnt lgkmcnt(7)
	v_mfma_f32_32x32x16_bf16 v[34:49], v[146:149], v[134:137], v[34:49]
	s_waitcnt lgkmcnt(6)
	v_mfma_f32_32x32x16_bf16 v[50:65], v[150:153], v[134:137], v[50:65]
	s_mov_b32 s41, 0
	s_cmp_lg_u32 s7, 0
	s_cbranch_scc1 .Lat_first_A1

; #define LAS __attribute__((address_space(3)))
; __device__ __forceinline__ void attn_phase(LAS unsigned char* lds, const bf16_t* __restrict__ Q, const bf16_t* __restrict__ KN, const bf16_t* __restrict__ KR,
;                                            const bf16_t* __restrict__ VT, bf16_t* AO, int vcu, int G, int tid, int lane, int wave) {
;     ...
;                 if (more) { LAS unsigned char* nb = lds + ((t + 1) & 1) * BUF;
;                     *(LAS u32x4*)(nb + kdst) = gk0; *(LAS u32x4*)(nb + kdst + 64 * KP * 2) = gk1; *(LAS u32x4*)(nb + rdst) = gr; *(LAS u32x4*)(nb + vdst) = gv0; *(LAS u32x4*)(nb + vdst + 128) = gv1; }
;                 __syncthreads();
;             }
.Lat_nostage:
	s_mov_b32 s8, s39
	s_cmp_lt_u32 s8, s36
	s_cbranch_scc0 .Lat_exit
	s_add_i32 s39, s8, 1
	s_bitcmp1_b32 s8, 0
	s_cselect_b32 s37, 0xac00, 0
	s_cselect_b32 s38, 0, 0xac00
	s_waitcnt lgkmcnt(0)
	s_cmp_lt_u32 s39, s36
	s_cbranch_scc0 .Lat_rot_nopf
	s_mov_b32 s40, s39
	s_mov_b32 s41, 0
	s_lshl_b64 s[14:15], s[40:41], 17
	s_add_u32 s14, s10, s14
	s_addc_u32 s15, s11, s15
	global_load_dwordx4 v[228:231], v198, s[14:15]
	s_add_u32 s14, s14, 0x10000
	s_addc_u32 s15, s15, 0
	global_load_dwordx4 v[232:235], v198, s[14:15]
	s_lshl_b64 s[14:15], s[40:41], 13
	v_lshl_add_u64 v[250:251], v[208:209], 0, s[14:15]
	s_lshl_b64 s[14:15], s[40:41], 8
	v_lshl_add_u64 v[252:253], v[210:211], 0, s[14:15]
	global_load_dwordx4 v[236:239], v[250:251], off
	global_load_dwordx4 v[240:243], v[252:253], off
	global_load_dwordx4 v[244:247], v[252:253], off offset:128
.Lat_rot_nopf:
	s_lshl_b32 s40, s8, 1
	s_cmp_lt_u32 s40, s33
	s_cbranch_scc1 .Lat_both_b
	s_cmp_eq_u32 s40, s33
	s_cbranch_scc1 .Lat_single_b
	s_barrier
	s_branch .Lat_tail
.Lat_exit:
	s_waitcnt lgkmcnt(0)
	s_barrier
	s_branch .LBB0_532
